# GLA scan V tile staged HBM->LDS by LDS-DMA (lane-linear image = transpose-read layout), section A hand-written; 4 ds_write_b128 + 4 register loads per thread-step removed
# speedup vs baseline: 1.0030x; 1.0030x over previous
; __device__ __forceinline__ unsigned pk2(float lo, float hi) { f32x2_t v = {lo, hi}; bf16x2_t b = __builtin_convertvector(v, bf16x2_t); return __builtin_bit_cast(unsigned, b); }
; __device__ __forceinline__ void scan_unit(const int unit, const Args& a, unsigned char* lds, const int mk_wid) {
;     ...
;     { const int l_ = MK_TID & 63, r32 = l_ & 31, hi = l_ >> 5; const float* up = a.in[dir ? 12 : 10] + (size_t)(8 * hi) * 512 + h * 128 + (wid & 3) * 32 + r32;
;       v4u w; w.x = pk2(up[0], up[512]); w.y = pk2(up[2 * 512], up[3 * 512]); w.z = pk2(up[4 * 512], up[5 * 512]); w.w = pk2(up[6 * 512], up[7 * 512]);
;       upf = __builtin_bit_cast(bf16x8, w); biasc = a.in[dir ? 13 : 11][h * 128 + (wid & 3) * 32 + r32]; }
;     u16* qe = (u16*)(lds + L_QE); u16* ke = (u16*)(lds + L_KE); u16* am = (u16*)(lds + L_AM);
;     float* las = (float*)(lds + L_LAS); float* gs = (float*)(lds + L_GS); float* dl = (float*)(lds + L_DL);
;     const int ldsb = (int)(uintptr_t)lds;
;     u16* ot = (u16*)(lds + L_LAS);
;     int pend_cc = -1;
;     ...
;     f32x16 S[4]; S[0] = f32x16{}; S[1] = f32x16{}; S[2] = f32x16{}; S[3] = f32x16{};
;     bf16x8 qraw[2], kraw[2], vraw[4]; bf16x8 lraw = bf16x8{};
;     ...
;     GLA_LOAD(0);
.LBB0_416:
	s_or_b64 exec, exec, s[22:23]
	s_mov_b32 s4, 0x2a00000
	s_and_b64 s[20:21], s[2:3], exec
	s_cselect_b32 s4, s4, 0x1aa00000
	s_add_u32 s4, s38, s4
	s_addc_u32 s9, s39, 0
	s_lshl_b64 s[20:21], s[18:19], 11
	s_lshl_b32 s18, s35, 1
	s_add_u32 s18, s4, s18
	s_addc_u32 s19, s9, 0
	s_lshr_b32 s4, s33, 8
	s_lshl_b32 s9, s4, 10
	s_add_i32 s44, s9, 0
	s_lshl_b32 s4, s4, 14
	s_add_i32 s9, 0, 0x16c00
	s_add_i32 s45, s9, s4
	s_lshl_b32 s22, s34, 2
	s_add_i32 s44, s44, 0x1ec00
	s_add_i32 s45, s45, s22
	s_lshl_b32 s22, s27, 1
	s_add_u32 s22, s38, s22
	s_addc_u32 s23, s39, 0
	s_add_u32 s22, s22, 0xd600000
	s_addc_u32 s23, s23, 0
	s_cmpk_lt_u32 s33, 0x100
	v_lshl_add_u64 v[152:153], v[0:1], 1, s[24:25]
	s_cselect_b64 s[24:25], -1, 0
	s_lshl_b32 s27, s70, 4
	s_and_b32 s46, s27, 0x3fffffe0
	s_lshl_b32 s27, s70, 5
	s_and_b32 s47, s27, 32
	s_cmp_lg_u32 0, -1
	s_cselect_b32 s27, 0, 0
	s_add_i32 s4, s27, s4
	s_lshl_b32 s26, s26, 9
	s_add_i32 s48, s4, s26
	v_mov_b32_e32 v155, 0
	s_waitcnt vmcnt(0)
	v_mov_b32_e32 v128, 0
	v_cvt_pk_bf16_f32 v108, v5, v7
	v_cvt_pk_bf16_f32 v109, v2, v8
	v_cvt_pk_bf16_f32 v110, v3, v4
	v_cvt_pk_bf16_f32 v111, v6, v9
	s_mov_b32 s34, -1
	s_add_i32 s48, s48, 0xc800
	s_add_i32 s49, s9, s72
	s_mov_b32 s50, 38
	s_movk_i32 s51, 0x110
	s_movk_i32 s52, 0x80
	s_add_i32 s53, 0, 0x1ec00
	s_mov_b32 s54, 0xbfb8aa3b
	s_add_i32 s55, 0, 0x1f400
	s_movk_i32 s56, 0x1100
	s_add_i32 s57, 0, 0x14800
	v_mov_b32_e32 v129, v128
	v_mov_b32_e32 v130, v128
	v_mov_b32_e32 v131, v128
	v_mov_b32_e32 v132, v128
	v_mov_b32_e32 v133, v128
	v_mov_b32_e32 v134, v128
	v_mov_b32_e32 v135, v128
	v_mov_b32_e32 v0, v155
	v_mov_b32_e32 v1, v155
	v_mov_b32_e32 v2, v155
	v_mov_b32_e32 v3, v155
	v_mov_b32_e32 v4, v155
	v_mov_b32_e32 v5, v155
	v_mov_b32_e32 v6, v155
	v_mov_b32_e32 v7, v155
	v_mov_b32_e32 v8, v155
	v_mov_b32_e32 v9, v155
	v_mov_b32_e32 v10, v155
	v_mov_b32_e32 v11, v155
	v_mov_b32_e32 v12, v155
	v_mov_b32_e32 v13, v155
	v_mov_b32_e32 v14, v155
	v_mov_b32_e32 v15, v155
	v_mov_b32_e32 v16, v155
	v_mov_b32_e32 v17, v155
	v_mov_b32_e32 v18, v155
	v_mov_b32_e32 v19, v155
	v_mov_b32_e32 v20, v155
	v_mov_b32_e32 v21, v155
	v_mov_b32_e32 v22, v155
	v_mov_b32_e32 v23, v155
	v_mov_b32_e32 v24, v155
	v_mov_b32_e32 v25, v155
	v_mov_b32_e32 v26, v155
	v_mov_b32_e32 v27, v155
	v_mov_b32_e32 v28, v155
	v_mov_b32_e32 v29, v155
	v_mov_b32_e32 v30, v155
	v_mov_b32_e32 v31, v155
	v_mov_b32_e32 v32, v155
	v_mov_b32_e32 v33, v155
	v_mov_b32_e32 v34, v155
	v_mov_b32_e32 v35, v155
	v_mov_b32_e32 v36, v155
	v_mov_b32_e32 v37, v155
	v_mov_b32_e32 v38, v155
	v_mov_b32_e32 v39, v155
	v_mov_b32_e32 v40, v155
	v_mov_b32_e32 v41, v155
	v_mov_b32_e32 v42, v155
	v_mov_b32_e32 v43, v155
	v_mov_b32_e32 v44, v155
	v_mov_b32_e32 v45, v155
	v_mov_b32_e32 v46, v155
	v_mov_b32_e32 v47, v155
	v_mov_b32_e32 v48, v155
	v_mov_b32_e32 v49, v155
	v_mov_b32_e32 v50, v155
	v_mov_b32_e32 v51, v155
	v_mov_b32_e32 v52, v155
	v_mov_b32_e32 v53, v155
	v_mov_b32_e32 v54, v155
	v_mov_b32_e32 v55, v155
	v_mov_b32_e32 v56, v155
	v_mov_b32_e32 v57, v155
	v_mov_b32_e32 v58, v155
	v_mov_b32_e32 v59, v155
	v_mov_b32_e32 v60, v155
	v_mov_b32_e32 v61, v155
	v_mov_b32_e32 v62, v155
	v_mov_b32_e32 v63, v155
	v_mbcnt_lo_u32_b32 v64, -1, 0
	v_mbcnt_hi_u32_b32 v64, -1, v64
	v_add_u32_e32 v64, s72, v64
	v_lshrrev_b32_e32 v65, 4, v64
	v_and_b32_e32 v67, 15, v64
	v_lshlrev_b32_e32 v67, 4, v67
	v_sub_u32_e32 v66, 63, v65
	v_cndmask_b32_e64 v66, v66, v65, s[2:3]
	v_add_u32_e32 v66, s12, v66
	v_lshl_add_u32 v245, v66, 10, v67
	v_add_u32_e32 v68, 32, v65
	v_sub_u32_e32 v69, 31, v65
	v_cndmask_b32_e64 v68, v69, v68, s[2:3]
	v_add_u32_e32 v68, s12, v68
	v_lshl_add_u32 v246, v68, 10, v67
	v_lshrrev_b32_e32 v65, 5, v64
	v_and_b32_e32 v67, 31, v64
	v_lshlrev_b32_e32 v67, 4, v67
	v_lshrrev_b32_e32 v65, 1, v64
	v_sub_u32_e32 v69, 63, v65
	v_cndmask_b32_e64 v68, v69, v65, s[2:3]
	v_add_u32_e32 v68, s12, v68
	v_and_b32_e32 v67, 1, v64
	v_lshlrev_b32_e32 v67, 4, v67
	v_lshl_add_u32 v251, v68, 6, v67
	v_mbcnt_lo_u32_b32 v66, -1, 0
	v_mbcnt_hi_u32_b32 v66, -1, v66
	v_bfe_u32 v67, v66, 4, 1
	v_lshlrev_b32_e32 v67, 3, v67
	v_bfe_u32 v68, v66, 2, 2
	v_add_u32_e32 v67, v67, v68
	s_and_b32 s96, s70, 3
	s_lshl_b32 s96, s96, 4
	v_add_u32_e32 v67, s96, v67
	v_lshrrev_b32_e32 v68, 5, v66
	v_lshlrev_b32_e32 v68, 6, v68
	v_and_b32_e32 v69, 3, v66
	v_lshl_add_u32 v68, v69, 4, v68
	s_lshr_b32 s96, s70, 2
	s_lshl_b32 s96, s96, 8
	v_add_u32_e32 v68, s96, v68
	v_sub_u32_e32 v69, 63, v67
	v_cndmask_b32_e64 v69, v69, v67, s[2:3]
	v_add_u32_e32 v69, s12, v69
	v_lshl_add_u32 v247, v69, 11, v68
	v_add_u32_e32 v248, 0x80, v247
	v_add_u32_e32 v67, 4, v67
	v_sub_u32_e32 v69, 63, v67
	v_cndmask_b32_e64 v69, v69, v67, s[2:3]
	v_add_u32_e32 v69, s12, v69
	v_lshl_add_u32 v249, v69, 11, v68
	v_add_u32_e32 v250, 0x80, v249
; __device__ __forceinline__ int v_st(int k, int c) { const int kk = (k & ~0xC) | ((k & 4) << 1) | ((k & 8) >> 1); return ((kk >> 3) * 4 + (c >> 5)) * 512 + ((kk & 7) * 32 + (c & 31)) * 2; }
; #define OPAQUE_TID(name) int name = MK_TID; asm volatile("" : "+v"(name))
; #define GLA_FLUSH() do { if (pend_cc >= 0) { OPAQUE_TID(tf_); const size_t rl0_ = (size_t)b * T + (size_t)(pend_cc - 4) * 64; \
;       _Pragma("unroll") for (int p = 0; p < 4; ++p) { const int idx_ = p * 512 + tf_, i_ = idx_ >> 5, c16_ = idx_ & 31; \
;           *(v4u*)(OUT + (rl0_ + (dir ? 63 - i_ : i_)) * 1024 + h * 256 + c16_ * 8) = *(const v4u*)(ot + i_ * 256 + c16_ * 8); } } } while (0)
; __device__ __forceinline__ void scan_unit(const int unit, const Args& a, unsigned char* lds, const int mk_wid) {
;     ...
;     f32x16 S[4]; S[0] = f32x16{}; S[1] = f32x16{}; S[2] = f32x16{}; S[3] = f32x16{};
;     bf16x8 qraw[2], kraw[2], vraw[4]; bf16x8 lraw = bf16x8{};
;     ...
;     GLA_LOAD(0);
;     for (int step = 0; step < 36; ++step) {
;         const int cc = GLA_CHUNK(step); const bool lat = cc >= 4;
;         GLA_FLUSH();
;         { OPAQUE_TID(t_);
; #pragma unroll
;           for (int p = 0; p < 2; ++p) { const int i_ = p * 32 + (t_ >> 4), c_ = (t_ & 15) * 8; *(bf16x8*)(qe + i_ * QP + c_) = qraw[p]; *(bf16x8*)(ke + i_ * QP + c_) = kraw[p]; }
; #pragma unroll
;           for (int p = 0; p < 4; ++p) { const int i_ = p * 16 + (t_ >> 5), c8 = t_ & 31; *(bf16x8*)(lds + L_V + (c8 >> 4) * 16384 + v_st(i_, (c8 & 15) * 8)) = vraw[p]; }
;           if (t_ < 128) *(bf16x8*)(lds + L_LR + (t_ >> 1) * 32 + (t_ & 1) * 16) = lraw; }
.LBB0_418:
	v_mbcnt_lo_u32_b32 v64, -1, 0
	v_mbcnt_hi_u32_b32 v64, -1, v64
	v_add_u32_e32 v64, s72, v64
	v_lshrrev_b32_e32 v65, 4, v64
	v_and_b32_e32 v66, 15, v64
	v_lshlrev_b32_e32 v66, 4, v66
	v_mad_u32_u24 v65, v65, s51, v66
	s_bitcmp1_b32 s8, 0
	s_cbranch_scc1 .Lscan_cc_rev
	s_mov_b32 s96, s5
	s_branch .Lscan_cc_done
.Lscan_cc_rev:
	s_cmp_gt_u32 s5, 3
	s_cbranch_scc1 .Lscan_cc_revlat
	s_sub_i32 s96, 3, s5
	s_branch .Lscan_cc_done
.Lscan_cc_revlat:
	s_sub_i32 s96, 39, s5
.Lscan_cc_done:
	s_lshl_b32 s96, s96, 17
	s_lshl_b32 s97, s70, 12
	s_add_i32 s97, s97, 0xc800
	s_waitcnt vmcnt(0)
	ds_write_b128 v65, v[128:131]
	ds_write_b128 v65, v[100:103] offset:17408
	ds_write_b128 v65, v[132:135] offset:8704
	ds_write_b128 v65, v[104:107] offset:26112
	s_cmp_lt_u32 s70, 2
	s_cbranch_scc0 .Lscan_nolrw
	v_lshrrev_b32_e32 v66, 1, v64
	v_lshlrev_b32_e32 v66, 5, v66
	v_and_b32_e32 v67, 1, v64
	v_lshl_add_u32 v66, v67, 4, v66
	v_add_u32_e32 v66, s53, v66
	ds_write_b128 v66, v[96:99]
.Lscan_nolrw:
	v_add_u32_e32 v66, s96, v247
	v_add_u32_e32 v67, s96, v248
	v_add_u32_e32 v68, s96, v249
	v_add_u32_e32 v69, s96, v250
	s_mov_b32 m0, s97
	s_nop 0
	global_load_lds_dwordx4 v66, s[16:17]
	s_add_i32 m0, s97, 0x400
	s_nop 0
	global_load_lds_dwordx4 v67, s[16:17]
	s_add_i32 m0, s97, 0x800
	s_nop 0
	global_load_lds_dwordx4 v68, s[16:17]
	s_add_i32 m0, s97, 0xc00
	s_nop 0
	global_load_lds_dwordx4 v69, s[16:17]
	s_cmp_lt_i32 s34, 0
	s_cbranch_scc1 .Lscan_noflush
	v_mbcnt_lo_u32_b32 v64, -1, 0
	v_mbcnt_hi_u32_b32 v64, -1, v64
	s_ashr_i32 s35, s34, 31
	v_add_u32_e32 v76, s72, v64
	s_lshl_b64 s[26:27], s[34:35], 6
	v_lshlrev_b32_e32 v64, 4, v76
	s_add_u32 s4, s26, s20
	v_and_b32_e32 v154, 0x1f0, v64
	v_ashrrev_i32_e32 v68, 5, v76
	s_addc_u32 s27, s27, s21
	v_add_u32_e32 v77, s9, v154
	v_sub_u32_e32 v69, 63, v68
	s_add_u32 s26, s4, 0xffffff00
	v_lshl_add_u32 v64, v68, 9, v77
	v_cndmask_b32_e64 v68, v69, v68, s[2:3]
	s_addc_u32 s27, s27, -1
	v_ashrrev_i32_e32 v69, 31, v68
	ds_read_b128 v[64:67], v64
	v_lshl_add_u64 v[68:69], s[26:27], 0, v[68:69]
	v_lshl_add_u64 v[72:73], s[18:19], 0, v[154:155]
	v_lshlrev_b64 v[68:69], 11, v[68:69]
	v_lshl_add_u64 v[74:75], v[72:73], 0, v[68:69]
	v_add_u32_e32 v68, 0x200, v76
	v_ashrrev_i32_e32 v78, 5, v68
	v_lshl_add_u32 v68, v78, 9, v77
	ds_read_b128 v[68:71], v68
	s_waitcnt lgkmcnt(1)
	global_store_dwordx4 v[74:75], v[64:67], off
	s_nop 1
	v_sub_u32_e32 v64, 63, v78
	v_cndmask_b32_e64 v64, v64, v78, s[2:3]
	v_ashrrev_i32_e32 v65, 31, v64
	v_lshl_add_u64 v[64:65], s[26:27], 0, v[64:65]
	v_lshlrev_b64 v[64:65], 11, v[64:65]
	v_lshl_add_u64 v[64:65], v[72:73], 0, v[64:65]
	s_waitcnt lgkmcnt(0)
	global_store_dwordx4 v[64:65], v[68:71], off
	v_add_u32_e32 v64, 0x400, v76
	s_nop 0
	v_ashrrev_i32_e32 v68, 5, v64
	v_sub_u32_e32 v69, 63, v68
	v_lshl_add_u32 v64, v68, 9, v77
	v_cndmask_b32_e64 v68, v69, v68, s[2:3]
	v_ashrrev_i32_e32 v69, 31, v68
	ds_read_b128 v[64:67], v64
	v_lshl_add_u64 v[68:69], s[26:27], 0, v[68:69]
	v_lshlrev_b64 v[68:69], 11, v[68:69]
	v_lshl_add_u64 v[74:75], v[72:73], 0, v[68:69]
	v_add_u32_e32 v68, 0x600, v76
	v_ashrrev_i32_e32 v76, 5, v68
	v_lshl_add_u32 v68, v76, 9, v77
	ds_read_b128 v[68:71], v68
	s_waitcnt lgkmcnt(1)
	global_store_dwordx4 v[74:75], v[64:67], off
	s_nop 1
	v_sub_u32_e32 v64, 63, v76
	v_cndmask_b32_e64 v64, v64, v76, s[2:3]
	v_ashrrev_i32_e32 v65, 31, v64
	v_lshl_add_u64 v[64:65], s[26:27], 0, v[64:65]
	v_lshlrev_b64 v[64:65], 11, v[64:65]
	v_lshl_add_u64 v[64:65], v[72:73], 0, v[64:65]
	s_waitcnt lgkmcnt(0)
	global_store_dwordx4 v[64:65], v[68:71], off

; __device__ __forceinline__ int v_st(int k, int c) { const int kk = (k & ~0xC) | ((k & 4) << 1) | ((k & 8) >> 1); return ((kk >> 3) * 4 + (c >> 5)) * 512 + ((kk & 7) * 32 + (c & 31)) * 2; }
; __device__ __forceinline__ float bf2f(short s) { return __uint_as_float(((unsigned)(unsigned short)s) << 16); }
; __device__ __forceinline__ float bf2f(u16 u) { return __uint_as_float((unsigned)u << 16); }
; __device__ __forceinline__ u16 f2bf(float f) { return (u16)(pk2(f, 0.f) & 0xffffu); }
; __device__ __forceinline__ void scan_unit(const int unit, const Args& a, unsigned char* lds, const int mk_wid) {
;     ...
;           u16* qcol = qe + (g * 16) * QP + c; u16* kcol = ke + (g * 16) * QP + c; unsigned char* kdb = lds + L_KD + v_st(g * 16, c);
; #pragma unroll
;           for (int ii = 0; ii < 16; ++ii) { const float bb = bl[ii] + off;
;               const float qf = bf2f(qcol[ii * QP]), kf = bf2f(kcol[ii * QP]);
;               const float e = __builtin_amdgcn_exp2f(bb * 1.4426950408889634f), ker = kf * __builtin_amdgcn_rcpf(e);
;               qcol[ii * QP] = f2bf(qf * (0.088388347648318440f * e));
;               kcol[ii * QP] = f2bf(ker);
;               *(u16*)(kdb + v_st(ii, 0)) = f2bf(ker * dlc); } }
;         if (step + 1 < 36) GLA_LOAD(step + 1);
.Lscan_c2_nodl:
	v_mov_b32_e32 v71, 0xffff0000
	s_waitcnt lgkmcnt(12)
	v_lshlrev_b32_e32 v218, 16, v202
	v_and_b32_e32 v219, v71, v202
	v_lshlrev_b32_e32 v220, 16, v210
	v_and_b32_e32 v221, v71, v210
	v_mul_f32_e32 v218, v170, v218
	v_mul_f32_e32 v219, v171, v219
	v_mul_f32_e32 v220, v186, v220
	v_mul_f32_e32 v221, v187, v221
	v_cvt_pk_bf16_f32 v224, v218, v219
	v_mul_f32_e32 v222, v92, v220
	v_mul_f32_e32 v223, v93, v221
	v_cvt_pk_bf16_f32 v225, v220, v221
	ds_write_b32 v94, v224
	ds_write_b32 v94, v225 offset:17408
	v_cvt_pk_bf16_f32 v226, v222, v223
	ds_read_b32 v209, v68 offset:1904
	ds_read_b32 v217, v68 offset:19312
	ds_write_b32 v69, v226 offset:34816
	s_waitcnt lgkmcnt(15)
	v_lshlrev_b32_e32 v228, 16, v203
	v_and_b32_e32 v229, v71, v203
	v_lshlrev_b32_e32 v230, 16, v211
	v_and_b32_e32 v231, v71, v211
	v_mul_f32_e32 v228, v172, v228
	v_mul_f32_e32 v229, v173, v229
	v_mul_f32_e32 v230, v188, v230
	v_mul_f32_e32 v231, v189, v231
	v_cvt_pk_bf16_f32 v234, v228, v229
	v_mul_f32_e32 v232, v92, v230
	v_mul_f32_e32 v233, v93, v231
	v_cvt_pk_bf16_f32 v235, v230, v231
	ds_write_b32 v94, v234 offset:272
	ds_write_b32 v94, v235 offset:17680
	v_cvt_pk_bf16_f32 v236, v232, v233
	ds_write_b32 v69, v236 offset:34880
	s_waitcnt lgkmcnt(15)
	v_lshlrev_b32_e32 v218, 16, v204
	v_and_b32_e32 v219, v71, v204
	v_lshlrev_b32_e32 v220, 16, v212
	v_and_b32_e32 v221, v71, v212
	v_mul_f32_e32 v218, v174, v218
	v_mul_f32_e32 v219, v175, v219
	v_mul_f32_e32 v220, v190, v220
	v_mul_f32_e32 v221, v191, v221
	v_cvt_pk_bf16_f32 v224, v218, v219
	v_mul_f32_e32 v222, v92, v220
	v_mul_f32_e32 v223, v93, v221
	v_cvt_pk_bf16_f32 v225, v220, v221
	ds_write_b32 v94, v224 offset:544
	ds_write_b32 v94, v225 offset:17952
	v_cvt_pk_bf16_f32 v226, v222, v223
	ds_write_b32 v69, v226 offset:34944
	s_waitcnt lgkmcnt(15)
	v_lshlrev_b32_e32 v228, 16, v205
	v_and_b32_e32 v229, v71, v205
	v_lshlrev_b32_e32 v230, 16, v213
	v_and_b32_e32 v231, v71, v213
	v_mul_f32_e32 v228, v176, v228
	v_mul_f32_e32 v229, v177, v229
	v_mul_f32_e32 v230, v192, v230
	v_mul_f32_e32 v231, v193, v231
	v_cvt_pk_bf16_f32 v234, v228, v229
	v_mul_f32_e32 v232, v92, v230
	v_mul_f32_e32 v233, v93, v231
	v_cvt_pk_bf16_f32 v235, v230, v231
	ds_write_b32 v94, v234 offset:816
	ds_write_b32 v94, v235 offset:18224
	v_cvt_pk_bf16_f32 v236, v232, v233
	ds_write_b32 v69, v236 offset:35008
	s_waitcnt lgkmcnt(15)
	v_lshlrev_b32_e32 v218, 16, v206
	v_and_b32_e32 v219, v71, v206
	v_lshlrev_b32_e32 v220, 16, v214
	v_and_b32_e32 v221, v71, v214
	v_mul_f32_e32 v218, v178, v218
	v_mul_f32_e32 v219, v179, v219
	v_mul_f32_e32 v220, v194, v220
	v_mul_f32_e32 v221, v195, v221
	v_cvt_pk_bf16_f32 v224, v218, v219
	v_mul_f32_e32 v222, v92, v220
	v_mul_f32_e32 v223, v93, v221
	v_cvt_pk_bf16_f32 v225, v220, v221
	ds_write_b32 v94, v224 offset:1088
	ds_write_b32 v94, v225 offset:18496
	v_cvt_pk_bf16_f32 v226, v222, v223
	ds_write_b32 v69, v226 offset:36864
	s_waitcnt lgkmcnt(15)
	v_lshlrev_b32_e32 v228, 16, v207
	v_and_b32_e32 v229, v71, v207
	v_lshlrev_b32_e32 v230, 16, v215
	v_and_b32_e32 v231, v71, v215
	v_mul_f32_e32 v228, v180, v228
	v_mul_f32_e32 v229, v181, v229
	v_mul_f32_e32 v230, v196, v230
	v_mul_f32_e32 v231, v197, v231
	v_cvt_pk_bf16_f32 v234, v228, v229
	v_mul_f32_e32 v232, v92, v230
	v_mul_f32_e32 v233, v93, v231
	v_cvt_pk_bf16_f32 v235, v230, v231
	ds_write_b32 v94, v234 offset:1360
	ds_write_b32 v94, v235 offset:18768
	v_cvt_pk_bf16_f32 v236, v232, v233
	ds_write_b32 v69, v236 offset:36928
	s_waitcnt lgkmcnt(15)
	v_lshlrev_b32_e32 v218, 16, v208
	v_and_b32_e32 v219, v71, v208
	v_lshlrev_b32_e32 v220, 16, v216
	v_and_b32_e32 v221, v71, v216
	v_mul_f32_e32 v218, v182, v218
	v_mul_f32_e32 v219, v183, v219
	v_mul_f32_e32 v220, v198, v220
	v_mul_f32_e32 v221, v199, v221
	v_cvt_pk_bf16_f32 v224, v218, v219
	v_mul_f32_e32 v222, v92, v220
	v_mul_f32_e32 v223, v93, v221
	v_cvt_pk_bf16_f32 v225, v220, v221
	ds_write_b32 v94, v224 offset:1632
	ds_write_b32 v94, v225 offset:19040
	v_cvt_pk_bf16_f32 v226, v222, v223
	ds_write_b32 v69, v226 offset:36992
	s_waitcnt lgkmcnt(15)
	v_lshlrev_b32_e32 v228, 16, v209
	v_and_b32_e32 v229, v71, v209
	v_lshlrev_b32_e32 v230, 16, v217
	v_and_b32_e32 v231, v71, v217
	v_mul_f32_e32 v228, v184, v228
	v_mul_f32_e32 v229, v185, v229
	v_mul_f32_e32 v230, v200, v230
	v_mul_f32_e32 v231, v201, v231
	v_cvt_pk_bf16_f32 v234, v228, v229
	v_mul_f32_e32 v232, v92, v230
	v_mul_f32_e32 v233, v93, v231
	v_cvt_pk_bf16_f32 v235, v230, v231
	ds_write_b32 v94, v234 offset:1904
	ds_write_b32 v94, v235 offset:19312
	v_cvt_pk_bf16_f32 v236, v232, v233
	ds_write_b32 v69, v236 offset:37056
	s_waitcnt vmcnt(0)
	s_add_i32 s58, s5, 1
	s_cmp_eq_u32 s50, 3
	s_cbranch_scc1 .LBB0_435
	v_mbcnt_lo_u32_b32 v64, -1, 0
	v_mbcnt_hi_u32_b32 v64, -1, v64
	s_andn2_b64 vcc, exec, s[6:7]
	v_add_u32_e32 v70, s72, v64
	s_mov_b32 s34, s58
	s_cbranch_vccnz .LBB0_426
	s_cmp_gt_u32 s5, 2
	s_mov_b32 s34, s50
	s_cbranch_scc1 .LBB0_426
	s_sub_i32 s34, 2, s5
.LBB0_426:
	s_lshl_b32 s26, s34, 16
	s_lshl_b32 s35, s34, 12
	v_add_u32_e32 v64, s26, v245
	v_add_u32_e32 v65, s26, v246
	global_load_dwordx4 v[100:103], v64, s[14:15]
	s_cmp_lt_i32 s34, 4
	s_cbranch_scc1 .Lscan_pf_noq
	global_load_dwordx4 v[128:131], v64, s[22:23]
	global_load_dwordx4 v[104:107], v65, s[14:15]
	global_load_dwordx4 v[132:135], v65, s[22:23]
	s_branch .Lscan_pf_v

.Lscan_pf_v:
	s_cmp_lt_u32 s70, 2
	s_cbranch_scc0 .Lscan_pf_nolr
	v_add_u32_e32 v70, s35, v251
	v_mov_b32_e32 v71, 0
	v_lshl_add_u64 v[70:71], v[152:153], 0, v[70:71]
	global_load_dwordx4 v[96:99], v[70:71], off
